# v38 + hgrn even-step head: decay-total and row-ssq LDS reads issued at the top of the section, waits re-derived per use
# baseline (speedup 1.0000x reference)
.LBB0_523:
	ds_read_b128 v[32:35], v213
	ds_read_b128 v[36:39], v202
	ds_read_b32 v245, v168
	ds_read_b32 v247, v170
	ds_read_b32 v244, v174
	ds_read_b32 v246, v176
	ds_read2st64_b64 v[228:231], v159 offset1:1
	ds_read2st64_b64 v[232:235], v159 offset0:2 offset1:3
	ds_read2st64_b64 v[236:239], v159 offset0:4 offset1:5
	ds_read2st64_b64 v[240:243], v159 offset0:6 offset1:7
	v_sub_u32_e64 v40, s91, 1 clamp
	v_lshlrev_b32_e32 v40, 6, v40
	v_add_u32_e32 v53, s71, v40
	s_waitcnt lgkmcnt(9)
	v_lshlrev_b32_e32 v40, 16, v32
	v_and_b32_e32 v41, 0xffff0000, v32
	v_lshlrev_b32_e32 v42, 16, v33
	v_and_b32_e32 v43, 0xffff0000, v33
	v_lshlrev_b32_e32 v46, 16, v34
	v_and_b32_e32 v47, 0xffff0000, v34
	v_lshlrev_b32_e32 v48, 16, v35
	v_and_b32_e32 v49, 0xffff0000, v35
	s_waitcnt lgkmcnt(4)
	v_pk_add_f32 v[32:33], v[244:245], v[246:247]
	v_add_u32_e32 v54, 0xcc00, v160
	v_pk_fma_f32 v[44:45], v[32:33], s[70:71], v[92:93] op_sel_hi:[1,0,0]
	v_or_b32_e32 v33, v53, v93
	v_mul_f32_e32 v32, 0x4b800000, v45
	v_cmp_gt_f32_e32 vcc, s89, v45
	v_lshlrev_b32_e32 v86, 11, v33
	v_lshl_add_u64 v[50:51], v[80:81], 0, v[86:87]
	v_cndmask_b32_e32 v32, v45, v32, vcc
	v_rsq_f32_e32 v32, v32
	v_add_lshl_u32 v86, v53, v68, 11
	v_mul_f32_e32 v33, 0x45800000, v32
	v_cndmask_b32_e32 v52, v32, v33, vcc
	v_pk_mul_f32 v[32:33], v[52:53], v[40:41] op_sel_hi:[0,1]
	v_pk_mul_f32 v[34:35], v[52:53], v[42:43] op_sel_hi:[0,1]
	v_cvt_pk_bf16_f32 v32, v32, v33
	v_cvt_pk_bf16_f32 v33, v34, v35
	v_pk_mul_f32 v[34:35], v[52:53], v[46:47] op_sel_hi:[0,1]
	v_cvt_pk_bf16_f32 v34, v34, v35
	v_mul_f32_e32 v35, 0x4b800000, v44
	v_cmp_gt_f32_e32 vcc, s89, v44
	v_pk_mul_f32 v[40:41], v[52:53], v[48:49] op_sel_hi:[0,1]
	v_cvt_f32_f16_e32 v46, v194
	v_cndmask_b32_e32 v35, v44, v35, vcc
	v_rsq_f32_e32 v42, v35
	v_cvt_pk_bf16_f32 v35, v40, v41
	global_store_dwordx4 v[50:51], v[32:35], off
	v_cvt_f32_f16_sdwa v47, v194 dst_sel:DWORD dst_unused:UNUSED_PAD src0_sel:WORD_1
	s_waitcnt vmcnt(28)
	v_lshlrev_b32_e32 v48, 16, v200
	v_mul_f32_e32 v32, 0x45800000, v42
	v_cndmask_b32_e32 v40, v42, v32, vcc
	v_lshlrev_b32_e32 v32, 16, v36
	v_and_b32_e32 v33, 0xffff0000, v36
	v_lshlrev_b32_e32 v34, 16, v37
	v_and_b32_e32 v35, 0xffff0000, v37
	v_pk_mul_f32 v[32:33], v[40:41], v[32:33] op_sel_hi:[0,1]
	v_pk_mul_f32 v[34:35], v[40:41], v[34:35] op_sel_hi:[0,1]
	v_cvt_pk_bf16_f32 v32, v32, v33
	v_cvt_pk_bf16_f32 v33, v34, v35
	v_lshlrev_b32_e32 v34, 16, v38
	v_and_b32_e32 v35, 0xffff0000, v38
	v_lshlrev_b32_e32 v36, 16, v39
	v_and_b32_e32 v37, 0xffff0000, v39
	v_pk_mul_f32 v[34:35], v[40:41], v[34:35] op_sel_hi:[0,1]
	v_pk_mul_f32 v[36:37], v[40:41], v[36:37] op_sel_hi:[0,1]
	v_cvt_pk_bf16_f32 v34, v34, v35
	v_cvt_pk_bf16_f32 v35, v36, v37
	v_lshl_add_u64 v[40:41], v[80:81], 0, v[86:87]
	global_store_dwordx4 v[40:41], v[32:35], off
	v_and_b32_e32 v49, 0xffff0000, v200
	s_waitcnt lgkmcnt(3)
	v_add_f32_e32 v33, 0, v229
	v_cndmask_b32_e64 v34, v33, 0, s[64:65]
	v_add_f32_e32 v32, 0, v228
	v_add_f32_e32 v37, v231, v34
	v_cndmask_b32_e64 v35, v32, 0, s[64:65]
	v_cndmask_b32_e64 v34, v34, v37, s[0:1]
	v_add_f32_e32 v36, v230, v35
	s_waitcnt lgkmcnt(2)
	v_add_f32_e32 v37, v233, v34
	v_cndmask_b32_e64 v35, v35, v36, s[0:1]
	v_add_f32_e32 v32, v32, v230
	v_cndmask_b32_e64 v34, v34, v37, s[4:5]
	v_add_f32_e32 v33, v33, v231
	v_add_f32_e32 v36, v232, v35
	v_add_f32_e32 v37, v32, v232
	v_add_f32_e32 v32, v235, v34
	v_cndmask_b32_e64 v36, v35, v36, s[4:5]
	v_add_f32_e32 v38, v33, v233
	v_cndmask_b32_e64 v44, v34, v32, s[6:7]
	v_add_f32_e32 v39, v234, v36
	v_cndmask_b32_e64 v45, v36, v39, s[6:7]
	v_add_f32_e32 v40, v37, v234
	v_add_f32_e32 v41, v38, v235
	s_waitcnt lgkmcnt(1)
	v_add_f32_e32 v42, v236, v45
	v_add_f32_e32 v43, v237, v44
	v_cndmask_b32_e64 v43, v44, v43, s[8:9]
	v_cndmask_b32_e64 v42, v45, v42, s[8:9]
	v_add_f32_e32 v44, v238, v42
	v_add_f32_e32 v45, v239, v43
	v_cndmask_b32_e64 v43, v43, v45, s[10:11]
	v_cndmask_b32_e64 v42, v42, v44, s[10:11]
	s_waitcnt lgkmcnt(0)
	v_add_f32_e32 v44, v240, v42
	v_add_f32_e32 v45, v241, v43
	v_cndmask_b32_e64 v43, v43, v45, s[12:13]
	v_cndmask_b32_e64 v42, v42, v44, s[12:13]
	v_add_f32_e32 v44, v242, v42
	v_add_f32_e32 v45, v243, v43
	v_cndmask_b32_e64 v43, v43, v45, s[14:15]
	v_cndmask_b32_e64 v42, v42, v44, s[14:15]
	v_sub_f32_e32 v44, v42, v40
	v_sub_f32_e32 v45, v43, v41
	v_min_f32_e32 v42, 0x42e60000, v44
	v_min_f32_e32 v43, 0x42e60000, v45
	v_exp_f32_e32 v42, v42
	v_exp_f32_e32 v43, v43
	v_min_f32_e64 v44, -v44, s90
	v_min_f32_e64 v45, -v45, s90
	v_exp_f32_e32 v44, v44
	v_pk_mul_f32 v[42:43], v[42:43], v[46:47]
	v_exp_f32_e32 v45, v45
	v_rcp_f32_e32 v50, v46
	v_rcp_f32_e32 v51, v47
	v_pk_mul_f32 v[48:49], v[42:43], v[48:49]
	v_pk_add_f32 v[46:47], v[46:47], 1.0 op_sel_hi:[1,0] neg_lo:[1,0] neg_hi:[1,0]
	v_cvt_pk_bf16_f32 v52, v48, v49
	v_cvt_f32_f16_sdwa v49, v186 dst_sel:DWORD dst_unused:UNUSED_PAD src0_sel:WORD_1
	v_cvt_f32_f16_e32 v48, v186
	v_pk_mul_f32 v[44:45], v[50:51], v[44:45]
	s_andn2_b64 vcc, exec, s[64:65]
	v_pk_mul_f32 v[46:47], v[46:47], v[44:45]
	v_rcp_f32_e32 v50, v48
	v_rcp_f32_e32 v51, v49
	v_cvt_pk_bf16_f32 v53, v46, v47
	s_waitcnt vmcnt(28)
	v_lshlrev_b32_e32 v46, 16, v198
	v_and_b32_e32 v47, 0xffff0000, v198
	v_pk_mul_f32 v[42:43], v[42:43], v[48:49]
	v_pk_mul_f32 v[44:45], v[50:51], v[44:45]
	v_pk_mul_f32 v[46:47], v[42:43], v[46:47]
	s_nop 0
	v_cvt_pk_bf16_f32 v46, v46, v47
	ds_write2_b32 v54, v52, v46 offset1:68
	v_pk_add_f32 v[46:47], v[48:49], 1.0 op_sel_hi:[1,0] neg_lo:[1,0] neg_hi:[1,0]
	s_waitcnt vmcnt(22)
	v_lshlrev_b32_e32 v48, 16, v201
	v_pk_mul_f32 v[46:47], v[46:47], v[44:45]
	v_and_b32_e32 v49, 0xffff0000, v201
	v_cvt_pk_bf16_f32 v46, v46, v47
	ds_write2_b32 v199, v53, v46 offset1:68
	v_cvt_f32_f16_e32 v46, v181
	v_cvt_f32_f16_sdwa v47, v181 dst_sel:DWORD dst_unused:UNUSED_PAD src0_sel:WORD_1
	v_rcp_f32_e32 v50, v46
	v_pk_mul_f32 v[42:43], v[42:43], v[46:47]
	v_rcp_f32_e32 v51, v47
	v_pk_mul_f32 v[48:49], v[42:43], v[48:49]
	v_pk_add_f32 v[46:47], v[46:47], 1.0 op_sel_hi:[1,0] neg_lo:[1,0] neg_hi:[1,0]
	v_cvt_pk_bf16_f32 v52, v48, v49
	v_cvt_f32_f16_sdwa v49, v179 dst_sel:DWORD dst_unused:UNUSED_PAD src0_sel:WORD_1
	v_cvt_f32_f16_e32 v48, v179
	v_pk_mul_f32 v[44:45], v[50:51], v[44:45]
	v_rcp_f32_e32 v51, v49
	v_pk_mul_f32 v[46:47], v[46:47], v[44:45]
	v_rcp_f32_e32 v50, v48
	v_cvt_pk_bf16_f32 v53, v46, v47
	v_lshlrev_b32_e32 v46, 16, v185
	v_and_b32_e32 v47, 0xffff0000, v185
	v_pk_mul_f32 v[42:43], v[42:43], v[48:49]
	v_pk_mul_f32 v[44:45], v[50:51], v[44:45]
	v_pk_mul_f32 v[46:47], v[42:43], v[46:47]
	s_nop 0
	v_cvt_pk_bf16_f32 v46, v46, v47
	ds_write2_b32 v54, v52, v46 offset0:136 offset1:204
	v_pk_add_f32 v[46:47], v[48:49], 1.0 op_sel_hi:[1,0] neg_lo:[1,0] neg_hi:[1,0]
	s_waitcnt vmcnt(21)
	v_lshlrev_b32_e32 v48, 16, v196
	v_pk_mul_f32 v[46:47], v[46:47], v[44:45]
	v_and_b32_e32 v49, 0xffff0000, v196
	v_cvt_pk_bf16_f32 v46, v46, v47
	ds_write2_b32 v199, v53, v46 offset0:136 offset1:204
	v_cvt_f32_f16_e32 v46, v177
	v_cvt_f32_f16_sdwa v47, v177 dst_sel:DWORD dst_unused:UNUSED_PAD src0_sel:WORD_1
	v_add_u32_e32 v54, 0xd000, v160
	v_rcp_f32_e32 v50, v46
	v_pk_mul_f32 v[42:43], v[42:43], v[46:47]
	v_rcp_f32_e32 v51, v47
	v_pk_mul_f32 v[48:49], v[42:43], v[48:49]
	v_pk_add_f32 v[46:47], v[46:47], 1.0 op_sel_hi:[1,0] neg_lo:[1,0] neg_hi:[1,0]
	v_cvt_pk_bf16_f32 v52, v48, v49
	v_cvt_f32_f16_sdwa v49, v173 dst_sel:DWORD dst_unused:UNUSED_PAD src0_sel:WORD_1
	v_cvt_f32_f16_e32 v48, v173
	v_pk_mul_f32 v[44:45], v[50:51], v[44:45]
	v_rcp_f32_e32 v51, v49
	v_pk_mul_f32 v[46:47], v[46:47], v[44:45]
	v_rcp_f32_e32 v50, v48
	v_cvt_pk_bf16_f32 v53, v46, v47
	s_waitcnt vmcnt(20)
	v_lshlrev_b32_e32 v46, 16, v187
	v_and_b32_e32 v47, 0xffff0000, v187
	v_pk_mul_f32 v[42:43], v[42:43], v[48:49]
	v_pk_mul_f32 v[44:45], v[50:51], v[44:45]
	v_pk_mul_f32 v[46:47], v[42:43], v[46:47]
	s_nop 0
	v_cvt_pk_bf16_f32 v46, v46, v47
	ds_write2_b32 v54, v52, v46 offset0:16 offset1:84
	v_pk_add_f32 v[46:47], v[48:49], 1.0 op_sel_hi:[1,0] neg_lo:[1,0] neg_hi:[1,0]
	v_add_u32_e32 v52, 0x400, v199
	v_pk_mul_f32 v[46:47], v[46:47], v[44:45]
	v_lshlrev_b32_e32 v48, 16, v167
	v_cvt_pk_bf16_f32 v46, v46, v47
	ds_write2_b32 v52, v53, v46 offset0:16 offset1:84
	v_cvt_f32_f16_e32 v46, v166
	v_cvt_f32_f16_sdwa v47, v166 dst_sel:DWORD dst_unused:UNUSED_PAD src0_sel:WORD_1
	v_and_b32_e32 v49, 0xffff0000, v167
	v_rcp_f32_e32 v50, v46
	v_pk_mul_f32 v[42:43], v[42:43], v[46:47]
	v_rcp_f32_e32 v51, v47
	v_pk_mul_f32 v[48:49], v[42:43], v[48:49]
	v_pk_add_f32 v[46:47], v[46:47], 1.0 op_sel_hi:[1,0] neg_lo:[1,0] neg_hi:[1,0]
	v_cvt_pk_bf16_f32 v53, v48, v49
	v_cvt_f32_f16_sdwa v49, v164 dst_sel:DWORD dst_unused:UNUSED_PAD src0_sel:WORD_1
	v_cvt_f32_f16_e32 v48, v164
	v_pk_mul_f32 v[44:45], v[50:51], v[44:45]
	v_rcp_f32_e32 v51, v49
	v_pk_mul_f32 v[46:47], v[46:47], v[44:45]
	v_rcp_f32_e32 v50, v48
	v_cvt_pk_bf16_f32 v55, v46, v47
	v_lshlrev_b32_e32 v46, 16, v165
	v_and_b32_e32 v47, 0xffff0000, v165
	v_pk_mul_f32 v[42:43], v[42:43], v[48:49]
	s_nop 0
	v_pk_mul_f32 v[42:43], v[42:43], v[46:47]
	s_nop 0
	v_cvt_pk_bf16_f32 v42, v42, v43
	ds_write2_b32 v54, v53, v42 offset0:152 offset1:220
	v_pk_mul_f32 v[42:43], v[50:51], v[44:45]
	v_pk_add_f32 v[44:45], v[48:49], 1.0 op_sel_hi:[1,0] neg_lo:[1,0] neg_hi:[1,0]
	s_nop 0
	v_pk_mul_f32 v[42:43], v[44:45], v[42:43]
	s_nop 0
	v_cvt_pk_bf16_f32 v42, v42, v43
	v_cndmask_b32_e64 v43, 0, 1, s[64:65]
	v_cmp_ne_u32_e64 s[52:53], 1, v43
	ds_write2_b32 v52, v55, v42 offset0:152 offset1:220
	s_cbranch_vccnz .LBB0_525
	v_add_f32_e32 v33, v41, v237
	v_add_f32_e32 v32, v40, v236
	v_add_f32_e32 v33, v33, v239
	v_add_f32_e32 v32, v32, v238
	v_add_f32_e32 v33, v33, v241
	v_add_f32_e32 v32, v32, v240
	v_add_f32_e32 v35, v33, v243
	v_add_f32_e32 v34, v32, v242
	v_exp_f32_e32 v32, v34
	v_exp_f32_e32 v33, v35
	v_sub_f32_e32 v34, v34, v40
	v_sub_f32_e32 v35, v35, v41
	v_exp_f32_e32 v34, v34
	v_exp_f32_e32 v35, v35
	v_exp_f32_e32 v36, v40
	v_exp_f32_e32 v37, v41
	ds_write_b64 v169, v[32:33]
	ds_write_b64 v171, v[34:35]
	ds_write_b64 v172, v[36:37]
	s_waitcnt lgkmcnt(0)
